# XCD barrier: leaders leave without waiting for the acknowledgement of their own TOPGEN/XGEN bumps
# baseline (speedup 1.0000x reference)
; __device__ __forceinline__ unsigned xb_ld(unsigned* p)              { return __hip_atomic_load(p, __ATOMIC_RELAXED, __HIP_MEMORY_SCOPE_AGENT); }
; __device__ __forceinline__ unsigned xb_add(unsigned* p, unsigned v) { return __hip_atomic_fetch_add(p, v, __ATOMIC_RELAXED, __HIP_MEMORY_SCOPE_AGENT); }
; #define XB_SPIN(cond, bar) do { unsigned _sp = 0; while (cond) { __builtin_amdgcn_s_sleep(1); \
;     if ((++_sp & 255u) == 0u) { if (xb_ld(&(bar)[XB_TMO])) break; if (_sp > XB_SPIN_CAP) { atomicAdd(&(bar)[XB_TMO], 1u); break; } } } } while (0)
; __device__ __forceinline__ void xcd_barrier(const XcdBarrier& b) {
;     ...
;             if (og + 1u == (tg + 1u) * nx) xb_add(&bar[XB_TOPGEN], 1u);
;             else XB_SPIN(xb_ld(&bar[XB_TOPGEN]) == tg, bar);
;             __builtin_amdgcn_fence(__ATOMIC_ACQUIRE, "agent");
;             xb_add(&bar[XB_XGEN(b.x)], 1u);
;             asm volatile("s_waitcnt vmcnt(0)" ::: "memory");
.Lxs0_136:
	s_or_b64 exec, exec, s[4:5]
	s_mov_b64 s[4:5], exec
	v_mbcnt_lo_u32_b32 v0, s4, 0
	v_mbcnt_hi_u32_b32 v0, s5, v0
	v_cmp_eq_u32_e32 vcc, 0, v0
	s_nop 0
	s_nop 0
	s_and_saveexec_b64 s[6:7], vcc
	s_cbranch_execz .Lxs0_138
	s_bcnt1_i32_b64 s4, s[4:5]
	v_mov_b32_e32 v0, 0x2000
	v_mov_b32_e32 v1, s4
	s_nop 0
.Lxs0_138:
	s_or_b64 exec, exec, s[6:7]
	s_nop 0
